# S5 item prologue: all 32 Bbar fragment loads issued up front (immediate offsets) instead of 16 dependent round trips
# baseline (speedup 1.0000x reference)
.LBB0_649:
	s_or_b64 exec, exec, s[20:21]
	v_mul_f32_e32 v3, 0.5, v9
	v_mul_f32_e32 v4, 0x3f22f983, v3
	v_rndne_f32_e32 v7, v4
	v_fmac_f32_e32 v3, 0xbfc90000, v7
	v_fmac_f32_e32 v3, 0xb9fda000, v7
	v_fmac_f32_e32 v3, 0xb3a22169, v7
	v_mov_b32_e32 v6, 0xb94ca1f9
	v_mov_b32_e32 v9, 0x3c08839e
	v_cvt_i32_f32_e32 v7, v7
	v_mul_f32_e32 v4, v3, v3
	v_mul_f32_e32 v5, v3, v4
	v_fmac_f32_e32 v9, v4, v6
	v_mov_b32_e32 v6, 0xbe2aaaa3
	v_and_b32_e32 v7, 3, v7
	v_fmac_f32_e32 v6, v4, v9
	v_fmac_f32_e32 v3, v5, v6
	v_mov_b32_e32 v5, 0x37ccf5ce
	v_mov_b32_e32 v6, 0xbab6061a
	v_mov_b32_e32 v9, 0x3d2aaaa5
	v_cmp_ne_u32_e32 vcc, 0, v7
	s_and_saveexec_b64 s[20:21], vcc
	v_fmac_f32_e32 v6, v4, v5
	v_mul_f32_e32 v10, v4, v4
	v_fmac_f32_e32 v9, v4, v6
	v_fma_f32 v4, v4, -0.5, 1.0
	v_fmac_f32_e32 v4, v10, v9
	v_cmp_eq_u32_e32 vcc, 2, v7
	s_nop 1
	v_cndmask_b32_e32 v3, v4, v3, vcc
	v_cmp_eq_u32_e32 vcc, 1, v7
	s_nop 1
	v_cndmask_b32_e64 v3, -v3, v4, vcc
	s_or_b64 exec, exec, s[20:21]
	v_mul_f32_e32 v4, v0, v8
	v_mul_f32_e32 v5, 0x3fb8aa3b, v4
	v_rndne_f32_e32 v5, v5
	v_fmamk_f32 v6, v5, 0xbf317218, v4
	v_fmac_f32_e32 v6, 0x3102e308, v5
	v_mov_b32_e32 v7, 0x3ab69700
	s_mov_b32 s20, 0x43000000
	v_fmamk_f32 v7, v6, 0x395133b1, v7
	v_cmp_eq_f32_e32 vcc, s20, v5
	v_cvt_i32_f32_e32 v5, v5
	v_fmaak_f32 v7, v6, v7, 0x3c0887f9
	v_fmaak_f32 v7, v6, v7, 0x3d2aaa81
	v_fmaak_f32 v7, v6, v7, 0x3e2aaaab
	v_fma_f32 v7, v6, v7, 0.5
	v_ldexp_f32 v5, 1.0, v5
	v_mul_f32_e32 v7, v6, v7
	v_cndmask_b32_e32 v5, v5, v252, vcc
	v_fmac_f32_e32 v6, v6, v7
	v_add_f32_e32 v7, -1.0, v5
	v_fmac_f32_e32 v7, v5, v6
	v_add_f32_e32 v5, v7, v7
	s_mov_b32 s20, 0x42b17217
	v_cndmask_b32_e32 v5, v7, v5, vcc
	v_cmp_nlt_f32_e32 vcc, s20, v4
	v_mov_b32_e32 v6, v0
	s_lshl_b64 s[30:31], s[40:41], 10
	v_cndmask_b32_e32 v5, v253, v5, vcc
	v_cmp_ngt_f32_e32 vcc, s97, v4
	v_lshlrev_b32_e32 v178, 2, v58
	v_mov_b32_e32 v14, 0
	v_cndmask_b32_e32 v4, -1.0, v5, vcc
	v_add_f32_e32 v51, 1.0, v4
	v_mul_f32_e32 v84, v51, v2
	v_add_f32_e32 v2, v51, v51
	v_mul_f32_e32 v2, v2, v3
	v_fma_f32 v2, -v3, v2, v4
	v_mov_b32_e32 v3, v1
	v_pk_mul_f32 v[4:5], v[0:1], v[2:3]
	v_mov_b32_e32 v7, v84
	v_pk_fma_f32 v[4:5], v[0:1], v[6:7], v[4:5] op_sel:[0,0,1] op_sel_hi:[1,1,0]
	v_mov_b32_e32 v85, v2
	v_div_scale_f32 v3, s[20:21], v4, v4, v5
	v_rcp_f32_e32 v6, v3
	v_pk_mul_f32 v[0:1], v[0:1], v[84:85]
	v_mov_b32_e32 v15, 0
	v_sub_f32_e32 v0, v0, v1
	v_fma_f32 v7, -v3, v6, 1.0
	v_fmac_f32_e32 v6, v7, v6
	v_div_scale_f32 v7, vcc, v5, v4, v5
	v_mul_f32_e32 v8, v7, v6
	v_div_scale_f32 v1, s[20:21], v4, v4, v0
	v_fma_f32 v9, -v3, v8, v7
	v_rcp_f32_e32 v2, v1
	v_fmac_f32_e32 v8, v9, v6
	v_fma_f32 v3, -v3, v8, v7
	v_div_fmas_f32 v3, v3, v6, v8
	v_div_fixup_f32 v42, v3, v4, v5
	v_fma_f32 v3, -v1, v2, 1.0
	v_fmac_f32_e32 v2, v3, v2
	v_div_scale_f32 v3, vcc, v0, v4, v0
	v_mul_f32_e32 v5, v3, v2
	v_fma_f32 v6, -v1, v5, v3
	v_fmac_f32_e32 v5, v6, v2
	v_fma_f32 v1, -v1, v5, v3
	s_load_dwordx4 s[20:23], s[0:1], 0xc0
	v_div_fmas_f32 v1, v1, v2, v5
	v_div_fixup_f32 v43, v1, v4, v0
	v_or_b32_e32 v0, v189, v59
	v_lshlrev_b32_e32 v0, 2, v0
	ds_bpermute_b32 v9, v0, v42
	ds_bpermute_b32 v8, v0, v43
	v_mov_b32_e32 v1, s31
	v_or_b32_e32 v0, s30, v60
	s_waitcnt lgkmcnt(0)
	v_lshl_add_u64 v[32:33], s[20:21], 0, v[178:179]
	v_lshlrev_b64 v[0:1], 2, v[0:1]
	v_lshl_add_u64 v[34:35], s[22:23], 0, v[178:179]
	v_lshl_add_u64 v[10:11], v[32:33], 0, v[0:1]
	v_lshl_add_u64 v[12:13], v[34:35], 0, v[0:1]
	global_load_dwordx4 v[118:121], v[10:11], off
	global_load_dwordx4 v[122:125], v[12:13], off
	global_load_dwordx4 v[126:129], v[10:11], off offset:16
	global_load_dwordx4 v[130:133], v[12:13], off offset:16
	global_load_dwordx4 v[134:137], v[10:11], off offset:512
	global_load_dwordx4 v[138:141], v[12:13], off offset:512
	global_load_dwordx4 v[142:145], v[10:11], off offset:528
	global_load_dwordx4 v[146:149], v[12:13], off offset:528
	global_load_dwordx4 v[150:153], v[10:11], off offset:1024
	global_load_dwordx4 v[154:157], v[12:13], off offset:1024
	global_load_dwordx4 v[158:161], v[10:11], off offset:1040
	global_load_dwordx4 v[162:165], v[12:13], off offset:1040
	global_load_dwordx4 v[166:169], v[10:11], off offset:1536
	global_load_dwordx4 v[170:173], v[12:13], off offset:1536
	global_load_dwordx4 v[174:177], v[10:11], off offset:1552
	global_load_dwordx4 v[180:183], v[12:13], off offset:1552
	global_load_dwordx4 v[184:187], v[10:11], off offset:2048
	global_load_dwordx4 v[190:193], v[12:13], off offset:2048
	global_load_dwordx4 v[194:197], v[10:11], off offset:2064
	global_load_dwordx4 v[198:201], v[12:13], off offset:2064
	global_load_dwordx4 v[202:205], v[10:11], off offset:2560
	global_load_dwordx4 v[206:209], v[12:13], off offset:2560
	global_load_dwordx4 v[210:213], v[10:11], off offset:2576
	global_load_dwordx4 v[214:217], v[12:13], off offset:2576
	global_load_dwordx4 v[218:221], v[10:11], off offset:3072
	global_load_dwordx4 v[222:225], v[12:13], off offset:3072
	global_load_dwordx4 v[226:229], v[10:11], off offset:3088
	global_load_dwordx4 v[230:233], v[12:13], off offset:3088
	global_load_dwordx4 v[234:237], v[10:11], off offset:3584
	global_load_dwordx4 v[238:241], v[12:13], off offset:3584
	global_load_dwordx4 v[242:245], v[10:11], off offset:3600
	global_load_dwordx4 v[246:249], v[12:13], off offset:3600
	s_waitcnt vmcnt(0)
	v_mov_b32_e32 v4, v118
	v_mov_b32_e32 v5, v119
	v_mov_b32_e32 v6, v120
	v_mov_b32_e32 v7, v121
	v_mov_b32_e32 v0, v122
	v_mov_b32_e32 v1, v123
	v_mov_b32_e32 v2, v124
	v_mov_b32_e32 v3, v125
	s_and_saveexec_b64 s[20:21], s[10:11]
	s_cbranch_execz .LBB0_657
	s_and_saveexec_b64 s[22:23], s[14:15]
	s_xor_b64 s[22:23], exec, s[22:23]
	s_cbranch_execz .LBB0_654
	s_waitcnt vmcnt(1)
	v_mov_b32_e32 v16, v4
	s_waitcnt vmcnt(0)
	v_mov_b32_e32 v17, v0
	v_pk_mul_f32 v[16:17], v[16:17], v[8:9]
	s_nop 0
	v_add_f32_e32 v15, v16, v17

.LBB0_675:
	s_or_b64 exec, exec, s[20:21]
	s_waitcnt vmcnt(0)
	v_mov_b32_e32 v4, v126
	v_mov_b32_e32 v5, v127
	v_mov_b32_e32 v6, v128
	v_mov_b32_e32 v7, v129
	v_mov_b32_e32 v0, v130
	v_mov_b32_e32 v1, v131
	v_mov_b32_e32 v2, v132
	v_mov_b32_e32 v3, v133
	v_mov_b32_e32 v10, 0
	v_mov_b32_e32 v11, 0
	s_and_saveexec_b64 s[20:21], s[10:11]
	s_cbranch_execz .LBB0_681
	s_and_saveexec_b64 s[22:23], s[14:15]
	s_xor_b64 s[22:23], exec, s[22:23]
	s_cbranch_execz .LBB0_678
	s_waitcnt vmcnt(1)
	v_mov_b32_e32 v12, v4
	s_waitcnt vmcnt(0)
	v_mov_b32_e32 v13, v0
	v_pk_mul_f32 v[12:13], v[12:13], v[8:9]
	s_nop 0
	v_add_f32_e32 v11, v12, v13

.LBB0_699:
	s_or_b64 exec, exec, s[20:21]
	s_waitcnt vmcnt(1)
	v_or_b32_e32 v4, v189, v61
	v_lshlrev_b32_e32 v4, 2, v4
	s_waitcnt vmcnt(0)
	v_cvt_pk_bf16_f32 v3, v13, v12
	ds_bpermute_b32 v13, v4, v42
	ds_bpermute_b32 v12, v4, v43
	v_mov_b32_e32 v5, s31
	v_or_b32_e32 v4, s30, v62
	v_lshlrev_b64 v[4:5], 2, v[4:5]
	v_cvt_pk_bf16_f32 v0, v15, v14
	v_lshl_add_u64 v[14:15], v[32:33], 0, v[4:5]
	v_cvt_pk_bf16_f32 v1, v17, v16
	v_cvt_pk_bf16_f32 v2, v11, v10
	v_lshl_add_u64 v[16:17], v[34:35], 0, v[4:5]
	s_waitcnt vmcnt(0)
	v_mov_b32_e32 v8, v134
	v_mov_b32_e32 v9, v135
	v_mov_b32_e32 v10, v136
	v_mov_b32_e32 v11, v137
	v_mov_b32_e32 v4, v138
	v_mov_b32_e32 v5, v139
	v_mov_b32_e32 v6, v140
	v_mov_b32_e32 v7, v141
	v_mov_b32_e32 v18, 0
	v_mov_b32_e32 v19, 0
	s_and_saveexec_b64 s[20:21], s[10:11]
	s_cbranch_execz .LBB0_705
	s_and_saveexec_b64 s[22:23], s[14:15]
	s_xor_b64 s[22:23], exec, s[22:23]
	s_cbranch_execz .LBB0_702
	s_waitcnt vmcnt(1)
	v_mov_b32_e32 v20, v8
	s_waitcnt vmcnt(0)
	v_mov_b32_e32 v21, v4
	s_waitcnt lgkmcnt(0)
	v_pk_mul_f32 v[20:21], v[20:21], v[12:13]
	s_nop 0
	v_add_f32_e32 v19, v20, v21

.LBB0_723:
	s_or_b64 exec, exec, s[20:21]
	s_waitcnt vmcnt(0)
	v_mov_b32_e32 v8, v142
	v_mov_b32_e32 v9, v143
	v_mov_b32_e32 v10, v144
	v_mov_b32_e32 v11, v145
	v_mov_b32_e32 v4, v146
	v_mov_b32_e32 v5, v147
	v_mov_b32_e32 v6, v148
	v_mov_b32_e32 v7, v149
	v_mov_b32_e32 v14, 0
	v_mov_b32_e32 v15, 0
	s_and_saveexec_b64 s[20:21], s[10:11]
	s_cbranch_execz .LBB0_729
	s_and_saveexec_b64 s[22:23], s[14:15]
	s_xor_b64 s[22:23], exec, s[22:23]
	s_cbranch_execz .LBB0_726
	s_waitcnt vmcnt(1)
	v_mov_b32_e32 v16, v8
	s_waitcnt vmcnt(0)
	v_mov_b32_e32 v17, v4
	s_waitcnt lgkmcnt(0)
	v_pk_mul_f32 v[16:17], v[16:17], v[12:13]
	s_nop 0
	v_add_f32_e32 v15, v16, v17

.LBB0_747:
	s_or_b64 exec, exec, s[20:21]
	s_waitcnt vmcnt(1)
	v_or_b32_e32 v8, v189, v63
	v_lshlrev_b32_e32 v8, 2, v8
	s_waitcnt vmcnt(0)
	v_cvt_pk_bf16_f32 v7, v17, v16
	ds_bpermute_b32 v17, v8, v42
	ds_bpermute_b32 v16, v8, v43
	v_mov_b32_e32 v9, s31
	v_or_b32_e32 v8, s30, v64
	v_lshlrev_b64 v[8:9], 2, v[8:9]
	v_cvt_pk_bf16_f32 v4, v19, v18
	v_lshl_add_u64 v[18:19], v[32:33], 0, v[8:9]
	v_cvt_pk_bf16_f32 v5, v21, v20
	v_cvt_pk_bf16_f32 v6, v15, v14
	v_lshl_add_u64 v[20:21], v[34:35], 0, v[8:9]
	s_waitcnt lgkmcnt(2)
	s_waitcnt vmcnt(0)
	v_mov_b32_e32 v12, v150
	v_mov_b32_e32 v13, v151
	v_mov_b32_e32 v14, v152
	v_mov_b32_e32 v15, v153
	v_mov_b32_e32 v8, v154
	v_mov_b32_e32 v9, v155
	v_mov_b32_e32 v10, v156
	v_mov_b32_e32 v11, v157
	v_mov_b32_e32 v22, 0
	v_mov_b32_e32 v23, 0
	s_and_saveexec_b64 s[20:21], s[10:11]
	s_cbranch_execz .LBB0_753
	s_and_saveexec_b64 s[22:23], s[14:15]
	s_xor_b64 s[22:23], exec, s[22:23]
	s_cbranch_execz .LBB0_750
	s_waitcnt vmcnt(1)
	v_mov_b32_e32 v24, v12
	s_waitcnt vmcnt(0)
	v_mov_b32_e32 v25, v8
	s_waitcnt lgkmcnt(0)
	v_pk_mul_f32 v[24:25], v[24:25], v[16:17]
	s_nop 0
	v_add_f32_e32 v23, v24, v25

.LBB0_771:
	s_or_b64 exec, exec, s[20:21]
	s_waitcnt vmcnt(0)
	v_mov_b32_e32 v12, v158
	v_mov_b32_e32 v13, v159
	v_mov_b32_e32 v14, v160
	v_mov_b32_e32 v15, v161
	v_mov_b32_e32 v8, v162
	v_mov_b32_e32 v9, v163
	v_mov_b32_e32 v10, v164
	v_mov_b32_e32 v11, v165
	v_mov_b32_e32 v18, 0
	v_mov_b32_e32 v19, 0
	s_and_saveexec_b64 s[20:21], s[10:11]
	s_cbranch_execz .LBB0_777
	s_and_saveexec_b64 s[22:23], s[14:15]
	s_xor_b64 s[22:23], exec, s[22:23]
	s_cbranch_execz .LBB0_774
	s_waitcnt vmcnt(1)
	v_mov_b32_e32 v20, v12
	s_waitcnt vmcnt(0)
	v_mov_b32_e32 v21, v8
	s_waitcnt lgkmcnt(0)
	v_pk_mul_f32 v[20:21], v[20:21], v[16:17]
	s_nop 0
	v_add_f32_e32 v19, v20, v21

.LBB0_795:
	s_or_b64 exec, exec, s[20:21]
	s_waitcnt vmcnt(1)
	v_or_b32_e32 v12, v189, v65
	v_lshlrev_b32_e32 v12, 2, v12
	s_waitcnt vmcnt(0)
	v_cvt_pk_bf16_f32 v11, v21, v20
	ds_bpermute_b32 v21, v12, v42
	ds_bpermute_b32 v20, v12, v43
	v_mov_b32_e32 v13, s31
	v_or_b32_e32 v12, s30, v66
	v_lshlrev_b64 v[12:13], 2, v[12:13]
	v_cvt_pk_bf16_f32 v8, v23, v22
	v_lshl_add_u64 v[22:23], v[32:33], 0, v[12:13]
	v_cvt_pk_bf16_f32 v9, v25, v24
	v_cvt_pk_bf16_f32 v10, v19, v18
	v_lshl_add_u64 v[24:25], v[34:35], 0, v[12:13]
	s_waitcnt lgkmcnt(2)
	s_waitcnt vmcnt(0)
	v_mov_b32_e32 v16, v166
	v_mov_b32_e32 v17, v167
	v_mov_b32_e32 v18, v168
	v_mov_b32_e32 v19, v169
	v_mov_b32_e32 v12, v170
	v_mov_b32_e32 v13, v171
	v_mov_b32_e32 v14, v172
	v_mov_b32_e32 v15, v173
	v_mov_b32_e32 v26, 0
	v_mov_b32_e32 v27, 0
	s_and_saveexec_b64 s[20:21], s[10:11]
	s_cbranch_execz .LBB0_801
	s_and_saveexec_b64 s[22:23], s[14:15]
	s_xor_b64 s[22:23], exec, s[22:23]
	s_cbranch_execz .LBB0_798
	s_waitcnt vmcnt(1)
	v_mov_b32_e32 v28, v16
	s_waitcnt vmcnt(0)
	v_mov_b32_e32 v29, v12
	s_waitcnt lgkmcnt(0)
	v_pk_mul_f32 v[28:29], v[28:29], v[20:21]
	s_nop 0
	v_add_f32_e32 v27, v28, v29

.LBB0_819:
	s_or_b64 exec, exec, s[20:21]
	s_waitcnt vmcnt(0)
	v_mov_b32_e32 v16, v174
	v_mov_b32_e32 v17, v175
	v_mov_b32_e32 v18, v176
	v_mov_b32_e32 v19, v177
	v_mov_b32_e32 v12, v180
	v_mov_b32_e32 v13, v181
	v_mov_b32_e32 v14, v182
	v_mov_b32_e32 v15, v183
	v_mov_b32_e32 v22, 0
	v_mov_b32_e32 v23, 0
	s_and_saveexec_b64 s[20:21], s[10:11]
	s_cbranch_execz .LBB0_825
	s_and_saveexec_b64 s[22:23], s[14:15]
	s_xor_b64 s[22:23], exec, s[22:23]
	s_cbranch_execz .LBB0_822
	s_waitcnt vmcnt(1)
	v_mov_b32_e32 v24, v16
	s_waitcnt vmcnt(0)
	v_mov_b32_e32 v25, v12
	s_waitcnt lgkmcnt(0)
	v_pk_mul_f32 v[24:25], v[24:25], v[20:21]
	s_nop 0
	v_add_f32_e32 v23, v24, v25

.LBB0_843:
	s_or_b64 exec, exec, s[20:21]
	s_waitcnt vmcnt(1)
	v_or_b32_e32 v16, v189, v67
	v_lshlrev_b32_e32 v16, 2, v16
	s_waitcnt vmcnt(0)
	v_cvt_pk_bf16_f32 v15, v25, v24
	ds_bpermute_b32 v25, v16, v42
	ds_bpermute_b32 v24, v16, v43
	v_mov_b32_e32 v17, s31
	v_or_b32_e32 v16, s30, v68
	v_lshlrev_b64 v[16:17], 2, v[16:17]
	v_cvt_pk_bf16_f32 v12, v27, v26
	v_lshl_add_u64 v[26:27], v[32:33], 0, v[16:17]
	v_cvt_pk_bf16_f32 v13, v29, v28
	v_cvt_pk_bf16_f32 v14, v23, v22
	v_lshl_add_u64 v[28:29], v[34:35], 0, v[16:17]
	s_waitcnt lgkmcnt(2)
	s_waitcnt vmcnt(0)
	v_mov_b32_e32 v20, v184
	v_mov_b32_e32 v21, v185
	v_mov_b32_e32 v22, v186
	v_mov_b32_e32 v23, v187
	v_mov_b32_e32 v16, v190
	v_mov_b32_e32 v17, v191
	v_mov_b32_e32 v18, v192
	v_mov_b32_e32 v19, v193
	v_mov_b32_e32 v30, 0
	v_mov_b32_e32 v31, 0
	s_and_saveexec_b64 s[20:21], s[10:11]
	s_cbranch_execz .LBB0_849
	s_and_saveexec_b64 s[22:23], s[14:15]
	s_xor_b64 s[22:23], exec, s[22:23]
	s_cbranch_execz .LBB0_846
	s_waitcnt vmcnt(1)
	v_mov_b32_e32 v36, v20
	s_waitcnt vmcnt(0)
	v_mov_b32_e32 v37, v16
	s_waitcnt lgkmcnt(0)
	v_pk_mul_f32 v[36:37], v[36:37], v[24:25]
	s_nop 0
	v_add_f32_e32 v31, v36, v37

.LBB0_867:
	s_or_b64 exec, exec, s[20:21]
	s_waitcnt vmcnt(0)
	v_mov_b32_e32 v20, v194
	v_mov_b32_e32 v21, v195
	v_mov_b32_e32 v22, v196
	v_mov_b32_e32 v23, v197
	v_mov_b32_e32 v16, v198
	v_mov_b32_e32 v17, v199
	v_mov_b32_e32 v18, v200
	v_mov_b32_e32 v19, v201
	v_mov_b32_e32 v26, 0
	v_mov_b32_e32 v27, 0
	s_and_saveexec_b64 s[20:21], s[10:11]
	s_cbranch_execz .LBB0_873
	s_and_saveexec_b64 s[22:23], s[14:15]
	s_xor_b64 s[22:23], exec, s[22:23]
	s_cbranch_execz .LBB0_870
	s_waitcnt vmcnt(1)
	v_mov_b32_e32 v28, v20
	s_waitcnt vmcnt(0)
	v_mov_b32_e32 v29, v16
	s_waitcnt lgkmcnt(0)
	v_pk_mul_f32 v[28:29], v[28:29], v[24:25]
	s_nop 0
	v_add_f32_e32 v27, v28, v29

.LBB0_891:
	s_or_b64 exec, exec, s[20:21]
	s_waitcnt vmcnt(1)
	v_or_b32_e32 v20, v189, v69
	v_lshlrev_b32_e32 v20, 2, v20
	s_waitcnt vmcnt(0)
	v_cvt_pk_bf16_f32 v19, v29, v28
	ds_bpermute_b32 v29, v20, v42
	ds_bpermute_b32 v28, v20, v43
	v_mov_b32_e32 v21, s31
	v_or_b32_e32 v20, s30, v70
	v_lshlrev_b64 v[20:21], 2, v[20:21]
	v_cvt_pk_bf16_f32 v16, v31, v30
	v_lshl_add_u64 v[30:31], v[32:33], 0, v[20:21]
	v_cvt_pk_bf16_f32 v17, v37, v36
	v_cvt_pk_bf16_f32 v18, v27, v26
	v_lshl_add_u64 v[36:37], v[34:35], 0, v[20:21]
	s_waitcnt lgkmcnt(2)
	s_waitcnt vmcnt(0)
	v_mov_b32_e32 v24, v202
	v_mov_b32_e32 v25, v203
	v_mov_b32_e32 v26, v204
	v_mov_b32_e32 v27, v205
	v_mov_b32_e32 v20, v206
	v_mov_b32_e32 v21, v207
	v_mov_b32_e32 v22, v208
	v_mov_b32_e32 v23, v209
	v_mov_b32_e32 v38, 0
	v_mov_b32_e32 v39, 0
	s_and_saveexec_b64 s[20:21], s[10:11]
	s_cbranch_execz .LBB0_897
	s_and_saveexec_b64 s[22:23], s[14:15]
	s_xor_b64 s[22:23], exec, s[22:23]
	s_cbranch_execz .LBB0_894
	s_waitcnt vmcnt(1)
	v_mov_b32_e32 v40, v24
	s_waitcnt vmcnt(0)
	v_mov_b32_e32 v41, v20
	s_waitcnt lgkmcnt(0)
	v_pk_mul_f32 v[40:41], v[40:41], v[28:29]
	s_nop 0
	v_add_f32_e32 v39, v40, v41

.LBB0_915:
	s_or_b64 exec, exec, s[20:21]
	s_waitcnt vmcnt(0)
	v_mov_b32_e32 v24, v210
	v_mov_b32_e32 v25, v211
	v_mov_b32_e32 v26, v212
	v_mov_b32_e32 v27, v213
	v_mov_b32_e32 v20, v214
	v_mov_b32_e32 v21, v215
	v_mov_b32_e32 v22, v216
	v_mov_b32_e32 v23, v217
	v_mov_b32_e32 v30, 0
	v_mov_b32_e32 v31, 0
	s_and_saveexec_b64 s[20:21], s[10:11]
	s_cbranch_execz .LBB0_921
	s_and_saveexec_b64 s[22:23], s[14:15]
	s_xor_b64 s[22:23], exec, s[22:23]
	s_cbranch_execz .LBB0_918
	s_waitcnt vmcnt(1)
	v_mov_b32_e32 v36, v24
	s_waitcnt vmcnt(0)
	v_mov_b32_e32 v37, v20
	s_waitcnt lgkmcnt(0)
	v_pk_mul_f32 v[36:37], v[36:37], v[28:29]
	s_nop 0
	v_add_f32_e32 v31, v36, v37

.LBB0_939:
	s_or_b64 exec, exec, s[20:21]
	s_waitcnt vmcnt(1)
	v_or_b32_e32 v24, v189, v71
	v_lshlrev_b32_e32 v24, 2, v24
	s_waitcnt vmcnt(0)
	v_cvt_pk_bf16_f32 v23, v37, v36
	ds_bpermute_b32 v37, v24, v42
	ds_bpermute_b32 v36, v24, v43
	v_mov_b32_e32 v25, s31
	v_or_b32_e32 v24, s30, v72
	v_lshlrev_b64 v[24:25], 2, v[24:25]
	v_cvt_pk_bf16_f32 v20, v39, v38
	v_lshl_add_u64 v[38:39], v[32:33], 0, v[24:25]
	v_cvt_pk_bf16_f32 v21, v41, v40
	v_cvt_pk_bf16_f32 v22, v31, v30
	v_lshl_add_u64 v[40:41], v[34:35], 0, v[24:25]
	s_waitcnt lgkmcnt(2)
	s_waitcnt vmcnt(0)
	v_mov_b32_e32 v28, v218
	v_mov_b32_e32 v29, v219
	v_mov_b32_e32 v30, v220
	v_mov_b32_e32 v31, v221
	v_mov_b32_e32 v24, v222
	v_mov_b32_e32 v25, v223
	v_mov_b32_e32 v26, v224
	v_mov_b32_e32 v27, v225
	v_mov_b32_e32 v44, 0
	v_mov_b32_e32 v45, 0
	s_and_saveexec_b64 s[20:21], s[10:11]
	s_cbranch_execz .LBB0_945
	s_and_saveexec_b64 s[22:23], s[14:15]
	s_xor_b64 s[22:23], exec, s[22:23]
	s_cbranch_execz .LBB0_942
	s_waitcnt vmcnt(1)
	v_mov_b32_e32 v46, v28
	s_waitcnt vmcnt(0)
	v_mov_b32_e32 v47, v24
	s_waitcnt lgkmcnt(0)
	v_pk_mul_f32 v[46:47], v[46:47], v[36:37]
	s_nop 0
	v_add_f32_e32 v45, v46, v47

.LBB0_963:
	s_or_b64 exec, exec, s[20:21]
	s_waitcnt vmcnt(0)
	v_mov_b32_e32 v28, v226
	v_mov_b32_e32 v29, v227
	v_mov_b32_e32 v30, v228
	v_mov_b32_e32 v31, v229
	v_mov_b32_e32 v24, v230
	v_mov_b32_e32 v25, v231
	v_mov_b32_e32 v26, v232
	v_mov_b32_e32 v27, v233
	v_mov_b32_e32 v38, 0
	v_mov_b32_e32 v39, 0
	s_and_saveexec_b64 s[20:21], s[10:11]
	s_cbranch_execz .LBB0_969
	s_and_saveexec_b64 s[22:23], s[14:15]
	s_xor_b64 s[22:23], exec, s[22:23]
	s_cbranch_execz .LBB0_966
	s_waitcnt vmcnt(1)
	v_mov_b32_e32 v40, v28
	s_waitcnt vmcnt(0)
	v_mov_b32_e32 v41, v24
	s_waitcnt lgkmcnt(0)
	v_pk_mul_f32 v[40:41], v[40:41], v[36:37]
	s_nop 0
	v_add_f32_e32 v39, v40, v41

.LBB0_987:
	s_or_b64 exec, exec, s[20:21]
	s_waitcnt vmcnt(1)
	v_or_b32_e32 v28, v189, v73
	v_lshlrev_b32_e32 v28, 2, v28
	s_waitcnt lgkmcnt(1)
	ds_bpermute_b32 v37, v28, v42
	s_waitcnt lgkmcnt(1)
	ds_bpermute_b32 v36, v28, v43
	v_mov_b32_e32 v29, s31
	v_or_b32_e32 v28, s30, v74
	v_lshlrev_b64 v[28:29], 2, v[28:29]
	s_waitcnt vmcnt(0)
	v_cvt_pk_bf16_f32 v26, v39, v38
	v_lshl_add_u64 v[38:39], v[32:33], 0, v[28:29]
	v_cvt_pk_bf16_f32 v27, v41, v40
	v_lshl_add_u64 v[40:41], v[34:35], 0, v[28:29]
	s_waitcnt vmcnt(0)
	v_mov_b32_e32 v32, v234
	v_mov_b32_e32 v33, v235
	v_mov_b32_e32 v34, v236
	v_mov_b32_e32 v35, v237
	v_mov_b32_e32 v28, v238
	v_mov_b32_e32 v29, v239
	v_mov_b32_e32 v30, v240
	v_mov_b32_e32 v31, v241
	v_mov_b32_e32 v42, 0
	v_mov_b32_e32 v43, 0
	v_cvt_pk_bf16_f32 v24, v45, v44
	v_cvt_pk_bf16_f32 v25, v47, v46
	s_and_saveexec_b64 s[20:21], s[10:11]
	s_cbranch_execz .LBB0_993
	s_and_saveexec_b64 s[22:23], s[14:15]
	s_xor_b64 s[22:23], exec, s[22:23]
	s_cbranch_execz .LBB0_990
	s_waitcnt vmcnt(1)
	v_mov_b32_e32 v44, v32
	s_waitcnt vmcnt(0)
	v_mov_b32_e32 v45, v28
	s_waitcnt lgkmcnt(0)
	v_pk_mul_f32 v[44:45], v[44:45], v[36:37]
	s_nop 0
	v_add_f32_e32 v43, v44, v45

.LBB0_1011:
	s_or_b64 exec, exec, s[20:21]
	s_waitcnt vmcnt(0)
	v_mov_b32_e32 v32, v242
	v_mov_b32_e32 v33, v243
	v_mov_b32_e32 v34, v244
	v_mov_b32_e32 v35, v245
	v_mov_b32_e32 v28, v246
	v_mov_b32_e32 v29, v247
	v_mov_b32_e32 v30, v248
	v_mov_b32_e32 v31, v249
	v_mov_b32_e32 v38, 0
	v_mov_b32_e32 v39, 0
	s_and_saveexec_b64 s[20:21], s[10:11]
	s_cbranch_execz .LBB0_1017
	s_and_saveexec_b64 s[22:23], s[14:15]
	s_xor_b64 s[22:23], exec, s[22:23]
	s_cbranch_execz .LBB0_1014
	s_waitcnt vmcnt(1)
	v_mov_b32_e32 v40, v32
	s_waitcnt vmcnt(0)
	v_mov_b32_e32 v41, v28
	s_waitcnt lgkmcnt(0)
	v_pk_mul_f32 v[40:41], v[40:41], v[36:37]
	s_nop 0
	v_add_f32_e32 v39, v40, v41

.LBB0_1059:
	s_or_b64 exec, exec, s[12:13]
	v_mul_f32_e32 v15, 0.5, v6
	v_mul_f32_e32 v0, 0x3f22f983, v15
	v_rndne_f32_e32 v3, v0
	v_fmac_f32_e32 v15, 0xbfc90000, v3
	v_fmac_f32_e32 v15, 0xb9fda000, v3
	v_fmac_f32_e32 v15, 0xb3a22169, v3
	v_mov_b32_e32 v2, 0xb94ca1f9
	v_mov_b32_e32 v4, 0x3c08839e
	v_cvt_i32_f32_e32 v3, v3
	v_mul_f32_e32 v0, v15, v15
	v_mul_f32_e32 v1, v15, v0
	v_fmac_f32_e32 v4, v0, v2
	v_mov_b32_e32 v2, 0xbe2aaaa3
	v_and_b32_e32 v3, 3, v3
	v_fmac_f32_e32 v2, v0, v4
	v_fmac_f32_e32 v15, v1, v2
	v_mov_b32_e32 v1, 0x37ccf5ce
	v_mov_b32_e32 v2, 0xbab6061a
	v_mov_b32_e32 v4, 0x3d2aaaa5
	v_cmp_ne_u32_e32 vcc, 0, v3
	s_and_saveexec_b64 s[12:13], vcc
	v_fmac_f32_e32 v2, v0, v1
	v_mul_f32_e32 v5, v0, v0
	v_fmac_f32_e32 v4, v0, v2
	v_fma_f32 v0, v0, -0.5, 1.0
	v_fmac_f32_e32 v0, v5, v4
	v_cmp_eq_u32_e32 vcc, 2, v3
	s_nop 1
	v_cndmask_b32_e32 v1, v0, v15, vcc
	v_cmp_eq_u32_e32 vcc, 1, v3
	s_nop 1
	v_cndmask_b32_e64 v15, -v1, v0, vcc
	s_or_b64 exec, exec, s[12:13]
	s_load_dwordx4 s[24:27], s[0:1], 0xc0
	v_ashrrev_i32_e32 v42, 4, v56
	v_lshlrev_b32_e32 v0, 3, v42
	v_and_b32_e32 v52, 8, v0
	v_bfe_u32 v43, v56, 1, 3
	s_lshl_b64 s[16:17], s[10:11], 10
	v_lshlrev_b32_e32 v178, 2, v52
	v_lshl_or_b32 v0, v43, 4, s16
	v_mov_b32_e32 v1, s17
	s_waitcnt lgkmcnt(0)
	v_lshl_add_u64 v[32:33], s[24:25], 0, v[178:179]
	v_lshlrev_b64 v[0:1], 2, v[0:1]
	v_lshl_add_u64 v[34:35], s[26:27], 0, v[178:179]
	v_lshl_add_u64 v[10:11], v[32:33], 0, v[0:1]
	v_lshl_add_u64 v[12:13], v[34:35], 0, v[0:1]
	global_load_dwordx4 v[118:121], v[10:11], off
	global_load_dwordx4 v[122:125], v[12:13], off
	global_load_dwordx4 v[126:129], v[10:11], off offset:16
	global_load_dwordx4 v[130:133], v[12:13], off offset:16
	global_load_dwordx4 v[134:137], v[10:11], off offset:512
	global_load_dwordx4 v[138:141], v[12:13], off offset:512
	global_load_dwordx4 v[142:145], v[10:11], off offset:528
	global_load_dwordx4 v[146:149], v[12:13], off offset:528
	global_load_dwordx4 v[150:153], v[10:11], off offset:1024
	global_load_dwordx4 v[154:157], v[12:13], off offset:1024
	global_load_dwordx4 v[158:161], v[10:11], off offset:1040
	global_load_dwordx4 v[162:165], v[12:13], off offset:1040
	global_load_dwordx4 v[166:169], v[10:11], off offset:1536
	global_load_dwordx4 v[170:173], v[12:13], off offset:1536
	global_load_dwordx4 v[174:177], v[10:11], off offset:1552
	global_load_dwordx4 v[180:183], v[12:13], off offset:1552
	global_load_dwordx4 v[184:187], v[10:11], off offset:2048
	global_load_dwordx4 v[190:193], v[12:13], off offset:2048
	global_load_dwordx4 v[194:197], v[10:11], off offset:2064
	global_load_dwordx4 v[198:201], v[12:13], off offset:2064
	global_load_dwordx4 v[202:205], v[10:11], off offset:2560
	global_load_dwordx4 v[206:209], v[12:13], off offset:2560
	global_load_dwordx4 v[210:213], v[10:11], off offset:2576
	global_load_dwordx4 v[214:217], v[12:13], off offset:2576
	global_load_dwordx4 v[218:221], v[10:11], off offset:3072
	global_load_dwordx4 v[222:225], v[12:13], off offset:3072
	global_load_dwordx4 v[226:229], v[10:11], off offset:3088
	global_load_dwordx4 v[230:233], v[12:13], off offset:3088
	global_load_dwordx4 v[234:237], v[10:11], off offset:3584
	global_load_dwordx4 v[238:241], v[12:13], off offset:3584
	global_load_dwordx4 v[242:245], v[10:11], off offset:3600
	global_load_dwordx4 v[246:249], v[12:13], off offset:3600
	s_waitcnt vmcnt(0)
	v_mov_b32_e32 v4, v118
	v_mov_b32_e32 v5, v119
	v_mov_b32_e32 v6, v120
	v_mov_b32_e32 v7, v121
	v_mov_b32_e32 v0, v122
	v_mov_b32_e32 v1, v123
	v_mov_b32_e32 v2, v124
	v_mov_b32_e32 v3, v125
	v_mul_f32_e32 v16, v8, v16
	v_mul_f32_e32 v17, 0x3fb8aa3b, v16
	v_rndne_f32_e32 v17, v17
	v_fmamk_f32 v18, v17, 0xbf317218, v16
	v_fmac_f32_e32 v18, 0x3102e308, v17
	v_mov_b32_e32 v19, 0x3ab69700
	v_fmamk_f32 v19, v18, 0x395133b1, v19
	v_fmaak_f32 v19, v18, v19, 0x3c0887f9
	v_fmaak_f32 v19, v18, v19, 0x3d2aaa81
	v_cvt_i32_f32_e32 v20, v17
	v_fmaak_f32 v19, v18, v19, 0x3e2aaaab
	v_fma_f32 v19, v18, v19, 0.5
	v_mul_f32_e32 v19, v18, v19
	s_mov_b32 s10, 0x43000000
	v_fmac_f32_e32 v18, v18, v19
	v_ldexp_f32 v19, 1.0, v20
	v_cmp_eq_f32_e32 vcc, s10, v17
	s_mov_b32 s10, 0x42b17217
	v_cmp_lt_i32_e64 s[12:13], 31, v56
	v_cndmask_b32_e32 v17, v19, v252, vcc
	v_add_f32_e32 v19, -1.0, v17
	v_fmac_f32_e32 v19, v17, v18
	v_add_f32_e32 v17, v19, v19
	v_cndmask_b32_e32 v17, v19, v17, vcc
	v_cmp_nlt_f32_e32 vcc, s10, v16
	v_mov_b32_e32 v18, v8
	s_nop 0
	v_cndmask_b32_e32 v17, v253, v17, vcc
	v_cmp_ngt_f32_e32 vcc, s97, v16
	s_nop 1
	v_cndmask_b32_e32 v16, -1.0, v17, vcc
	v_add_f32_e32 v61, 1.0, v16
	v_mul_f32_e32 v58, v61, v14
	v_add_f32_e32 v14, v61, v61
	v_mul_f32_e32 v14, v14, v15
	v_fma_f32 v14, -v15, v14, v16
	v_mov_b32_e32 v15, v9
	v_pk_mul_f32 v[16:17], v[8:9], v[14:15]
	v_mov_b32_e32 v19, v58
	v_pk_fma_f32 v[16:17], v[8:9], v[18:19], v[16:17] op_sel:[0,0,1] op_sel_hi:[1,1,0]
	v_mov_b32_e32 v59, v14
	v_div_scale_f32 v15, s[10:11], v16, v16, v17
	v_rcp_f32_e32 v18, v15
	v_pk_mul_f32 v[8:9], v[8:9], v[58:59]
	v_fma_f32 v19, -v15, v18, 1.0
	v_fmac_f32_e32 v18, v19, v18
	v_div_scale_f32 v19, vcc, v17, v16, v17
	v_sub_f32_e32 v8, v8, v9
	v_mul_f32_e32 v20, v19, v18
	v_div_scale_f32 v9, s[10:11], v16, v16, v8
	v_fma_f32 v21, -v15, v20, v19
	v_rcp_f32_e32 v14, v9
	v_fmac_f32_e32 v20, v21, v18
	v_fma_f32 v15, -v15, v20, v19
	v_div_fmas_f32 v15, v15, v18, v20
	v_div_fixup_f32 v44, v15, v16, v17
	v_fma_f32 v15, -v9, v14, 1.0
	v_fmac_f32_e32 v14, v15, v14
	v_div_scale_f32 v15, vcc, v8, v16, v8
	v_mul_f32_e32 v17, v15, v14
	v_fma_f32 v18, -v9, v17, v15
	v_fmac_f32_e32 v17, v18, v14
	v_fma_f32 v9, -v9, v17, v15
	v_div_fmas_f32 v9, v9, v14, v17
	v_div_fixup_f32 v45, v9, v16, v8
	v_or_b32_e32 v8, v189, v43
	v_lshlrev_b32_e32 v8, 2, v8
	ds_bpermute_b32 v9, v8, v44
	ds_bpermute_b32 v8, v8, v45
	v_and_b32_e32 v14, 1, v56
	v_cmp_gt_i32_e64 s[10:11], 32, v56
	v_cmp_eq_u32_e32 vcc, 1, v14
	v_mov_b32_e32 v14, 0
	v_mov_b32_e32 v15, 0
	s_and_saveexec_b64 s[18:19], s[10:11]
	s_cbranch_execz .LBB0_1067
	s_and_saveexec_b64 s[20:21], vcc
	s_xor_b64 s[20:21], exec, s[20:21]
	s_cbranch_execz .LBB0_1064
	s_waitcnt vmcnt(1)
	v_mov_b32_e32 v16, v4
	s_waitcnt vmcnt(0)
	v_mov_b32_e32 v17, v0
	s_waitcnt lgkmcnt(0)
	v_pk_mul_f32 v[16:17], v[16:17], v[8:9]
	s_nop 0
	v_add_f32_e32 v15, v16, v17

.LBB0_1085:
	s_or_b64 exec, exec, s[18:19]
	s_waitcnt vmcnt(0)
	v_mov_b32_e32 v4, v126
	v_mov_b32_e32 v5, v127
	v_mov_b32_e32 v6, v128
	v_mov_b32_e32 v7, v129
	v_mov_b32_e32 v0, v130
	v_mov_b32_e32 v1, v131
	v_mov_b32_e32 v2, v132
	v_mov_b32_e32 v3, v133
	v_mov_b32_e32 v10, 0
	v_mov_b32_e32 v11, 0
	s_and_saveexec_b64 s[18:19], s[10:11]
	s_cbranch_execz .LBB0_1091
	s_and_saveexec_b64 s[20:21], vcc
	s_xor_b64 s[20:21], exec, s[20:21]
	s_cbranch_execz .LBB0_1088
	s_waitcnt vmcnt(1)
	v_mov_b32_e32 v12, v4
	s_waitcnt vmcnt(0)
	v_mov_b32_e32 v13, v0
	s_waitcnt lgkmcnt(0)
	v_pk_mul_f32 v[12:13], v[12:13], v[8:9]
	s_nop 0
	v_add_f32_e32 v11, v12, v13

.LBB0_1109:
	s_or_b64 exec, exec, s[18:19]
	s_waitcnt vmcnt(1)
	v_or_b32_e32 v4, 8, v43
	v_or_b32_e32 v5, v189, v4
	v_lshlrev_b32_e32 v5, 2, v5
	s_waitcnt vmcnt(0)
	v_cvt_pk_bf16_f32 v3, v13, v12
	ds_bpermute_b32 v13, v5, v44
	ds_bpermute_b32 v12, v5, v45
	v_lshl_or_b32 v4, v4, 4, s16
	v_mov_b32_e32 v5, s17
	v_lshlrev_b64 v[4:5], 2, v[4:5]
	v_cvt_pk_bf16_f32 v0, v15, v14
	v_lshl_add_u64 v[14:15], v[32:33], 0, v[4:5]
	v_cvt_pk_bf16_f32 v1, v17, v16
	v_cvt_pk_bf16_f32 v2, v11, v10
	v_lshl_add_u64 v[16:17], v[34:35], 0, v[4:5]
	s_waitcnt lgkmcnt(2)
	s_waitcnt vmcnt(0)
	v_mov_b32_e32 v8, v134
	v_mov_b32_e32 v9, v135
	v_mov_b32_e32 v10, v136
	v_mov_b32_e32 v11, v137
	v_mov_b32_e32 v4, v138
	v_mov_b32_e32 v5, v139
	v_mov_b32_e32 v6, v140
	v_mov_b32_e32 v7, v141
	v_mov_b32_e32 v18, 0
	v_mov_b32_e32 v19, 0
	s_and_saveexec_b64 s[18:19], s[10:11]
	s_cbranch_execz .LBB0_1115
	s_and_saveexec_b64 s[20:21], vcc
	s_xor_b64 s[20:21], exec, s[20:21]
	s_cbranch_execz .LBB0_1112
	s_waitcnt vmcnt(1)
	v_mov_b32_e32 v20, v8
	s_waitcnt vmcnt(0)
	v_mov_b32_e32 v21, v4
	s_waitcnt lgkmcnt(0)
	v_pk_mul_f32 v[20:21], v[20:21], v[12:13]
	s_nop 0
	v_add_f32_e32 v19, v20, v21

.LBB0_1133:
	s_or_b64 exec, exec, s[18:19]
	s_waitcnt vmcnt(0)
	v_mov_b32_e32 v8, v142
	v_mov_b32_e32 v9, v143
	v_mov_b32_e32 v10, v144
	v_mov_b32_e32 v11, v145
	v_mov_b32_e32 v4, v146
	v_mov_b32_e32 v5, v147
	v_mov_b32_e32 v6, v148
	v_mov_b32_e32 v7, v149
	v_mov_b32_e32 v14, 0
	v_mov_b32_e32 v15, 0
	s_and_saveexec_b64 s[18:19], s[10:11]
	s_cbranch_execz .LBB0_1139
	s_and_saveexec_b64 s[20:21], vcc
	s_xor_b64 s[20:21], exec, s[20:21]
	s_cbranch_execz .LBB0_1136
	s_waitcnt vmcnt(1)
	v_mov_b32_e32 v16, v8
	s_waitcnt vmcnt(0)
	v_mov_b32_e32 v17, v4
	s_waitcnt lgkmcnt(0)
	v_pk_mul_f32 v[16:17], v[16:17], v[12:13]
	s_nop 0
	v_add_f32_e32 v15, v16, v17

.LBB0_1157:
	s_or_b64 exec, exec, s[18:19]
	s_waitcnt vmcnt(1)
	v_or_b32_e32 v8, 16, v43
	v_or_b32_e32 v9, v189, v8
	v_lshlrev_b32_e32 v9, 2, v9
	s_waitcnt vmcnt(0)
	v_cvt_pk_bf16_f32 v7, v17, v16
	ds_bpermute_b32 v17, v9, v44
	ds_bpermute_b32 v16, v9, v45
	v_lshl_or_b32 v8, v8, 4, s16
	v_mov_b32_e32 v9, s17
	v_lshlrev_b64 v[8:9], 2, v[8:9]
	v_cvt_pk_bf16_f32 v4, v19, v18
	v_lshl_add_u64 v[18:19], v[32:33], 0, v[8:9]
	v_cvt_pk_bf16_f32 v5, v21, v20
	v_cvt_pk_bf16_f32 v6, v15, v14
	v_lshl_add_u64 v[20:21], v[34:35], 0, v[8:9]
	s_waitcnt lgkmcnt(2)
	s_waitcnt vmcnt(0)
	v_mov_b32_e32 v12, v150
	v_mov_b32_e32 v13, v151
	v_mov_b32_e32 v14, v152
	v_mov_b32_e32 v15, v153
	v_mov_b32_e32 v8, v154
	v_mov_b32_e32 v9, v155
	v_mov_b32_e32 v10, v156
	v_mov_b32_e32 v11, v157
	v_mov_b32_e32 v22, 0
	v_mov_b32_e32 v23, 0
	s_and_saveexec_b64 s[18:19], s[10:11]
	s_cbranch_execz .LBB0_1163
	s_and_saveexec_b64 s[20:21], vcc
	s_xor_b64 s[20:21], exec, s[20:21]
	s_cbranch_execz .LBB0_1160
	s_waitcnt vmcnt(1)
	v_mov_b32_e32 v24, v12
	s_waitcnt vmcnt(0)
	v_mov_b32_e32 v25, v8
	s_waitcnt lgkmcnt(0)
	v_pk_mul_f32 v[24:25], v[24:25], v[16:17]
	s_nop 0
	v_add_f32_e32 v23, v24, v25

.LBB0_1181:
	s_or_b64 exec, exec, s[18:19]
	s_waitcnt vmcnt(0)
	v_mov_b32_e32 v12, v158
	v_mov_b32_e32 v13, v159
	v_mov_b32_e32 v14, v160
	v_mov_b32_e32 v15, v161
	v_mov_b32_e32 v8, v162
	v_mov_b32_e32 v9, v163
	v_mov_b32_e32 v10, v164
	v_mov_b32_e32 v11, v165
	v_mov_b32_e32 v18, 0
	v_mov_b32_e32 v19, 0
	s_and_saveexec_b64 s[18:19], s[10:11]
	s_cbranch_execz .LBB0_1187
	s_and_saveexec_b64 s[20:21], vcc
	s_xor_b64 s[20:21], exec, s[20:21]
	s_cbranch_execz .LBB0_1184
	s_waitcnt vmcnt(1)
	v_mov_b32_e32 v20, v12
	s_waitcnt vmcnt(0)
	v_mov_b32_e32 v21, v8
	s_waitcnt lgkmcnt(0)
	v_pk_mul_f32 v[20:21], v[20:21], v[16:17]
	s_nop 0
	v_add_f32_e32 v19, v20, v21

.LBB0_1205:
	s_or_b64 exec, exec, s[18:19]
	s_waitcnt vmcnt(1)
	v_or_b32_e32 v12, 24, v43
	v_or_b32_e32 v13, v189, v12
	v_lshlrev_b32_e32 v13, 2, v13
	s_waitcnt vmcnt(0)
	v_cvt_pk_bf16_f32 v11, v21, v20
	ds_bpermute_b32 v21, v13, v44
	ds_bpermute_b32 v20, v13, v45
	v_lshl_or_b32 v12, v12, 4, s16
	v_mov_b32_e32 v13, s17
	v_lshlrev_b64 v[12:13], 2, v[12:13]
	v_cvt_pk_bf16_f32 v8, v23, v22
	v_lshl_add_u64 v[22:23], v[32:33], 0, v[12:13]
	v_cvt_pk_bf16_f32 v9, v25, v24
	v_cvt_pk_bf16_f32 v10, v19, v18
	v_lshl_add_u64 v[24:25], v[34:35], 0, v[12:13]
	s_waitcnt lgkmcnt(2)
	s_waitcnt vmcnt(0)
	v_mov_b32_e32 v16, v166
	v_mov_b32_e32 v17, v167
	v_mov_b32_e32 v18, v168
	v_mov_b32_e32 v19, v169
	v_mov_b32_e32 v12, v170
	v_mov_b32_e32 v13, v171
	v_mov_b32_e32 v14, v172
	v_mov_b32_e32 v15, v173
	v_mov_b32_e32 v26, 0
	v_mov_b32_e32 v27, 0
	s_and_saveexec_b64 s[18:19], s[10:11]
	s_cbranch_execz .LBB0_1211
	s_and_saveexec_b64 s[20:21], vcc
	s_xor_b64 s[20:21], exec, s[20:21]
	s_cbranch_execz .LBB0_1208
	s_waitcnt vmcnt(1)
	v_mov_b32_e32 v28, v16
	s_waitcnt vmcnt(0)
	v_mov_b32_e32 v29, v12
	s_waitcnt lgkmcnt(0)
	v_pk_mul_f32 v[28:29], v[28:29], v[20:21]
	s_nop 0
	v_add_f32_e32 v27, v28, v29

.LBB0_1229:
	s_or_b64 exec, exec, s[18:19]
	s_waitcnt vmcnt(0)
	v_mov_b32_e32 v16, v174
	v_mov_b32_e32 v17, v175
	v_mov_b32_e32 v18, v176
	v_mov_b32_e32 v19, v177
	v_mov_b32_e32 v12, v180
	v_mov_b32_e32 v13, v181
	v_mov_b32_e32 v14, v182
	v_mov_b32_e32 v15, v183
	v_mov_b32_e32 v22, 0
	v_mov_b32_e32 v23, 0
	s_and_saveexec_b64 s[18:19], s[10:11]
	s_cbranch_execz .LBB0_1235
	s_and_saveexec_b64 s[20:21], vcc
	s_xor_b64 s[20:21], exec, s[20:21]
	s_cbranch_execz .LBB0_1232
	s_waitcnt vmcnt(1)
	v_mov_b32_e32 v24, v16
	s_waitcnt vmcnt(0)
	v_mov_b32_e32 v25, v12
	s_waitcnt lgkmcnt(0)
	v_pk_mul_f32 v[24:25], v[24:25], v[20:21]
	s_nop 0
	v_add_f32_e32 v23, v24, v25

.LBB0_1253:
	s_or_b64 exec, exec, s[18:19]
	s_waitcnt vmcnt(1)
	v_or_b32_e32 v16, 32, v43
	v_or_b32_e32 v17, v189, v16
	v_lshlrev_b32_e32 v17, 2, v17
	s_waitcnt vmcnt(0)
	v_cvt_pk_bf16_f32 v15, v25, v24
	ds_bpermute_b32 v25, v17, v44
	ds_bpermute_b32 v24, v17, v45
	v_lshl_or_b32 v16, v16, 4, s16
	v_mov_b32_e32 v17, s17
	v_lshlrev_b64 v[16:17], 2, v[16:17]
	v_cvt_pk_bf16_f32 v12, v27, v26
	v_lshl_add_u64 v[26:27], v[32:33], 0, v[16:17]
	v_cvt_pk_bf16_f32 v13, v29, v28
	v_cvt_pk_bf16_f32 v14, v23, v22
	v_lshl_add_u64 v[28:29], v[34:35], 0, v[16:17]
	s_waitcnt lgkmcnt(2)
	s_waitcnt vmcnt(0)
	v_mov_b32_e32 v20, v184
	v_mov_b32_e32 v21, v185
	v_mov_b32_e32 v22, v186
	v_mov_b32_e32 v23, v187
	v_mov_b32_e32 v16, v190
	v_mov_b32_e32 v17, v191
	v_mov_b32_e32 v18, v192
	v_mov_b32_e32 v19, v193
	v_mov_b32_e32 v30, 0
	v_mov_b32_e32 v31, 0
	s_and_saveexec_b64 s[18:19], s[10:11]
	s_cbranch_execz .LBB0_1259
	s_and_saveexec_b64 s[20:21], vcc
	s_xor_b64 s[20:21], exec, s[20:21]
	s_cbranch_execz .LBB0_1256
	s_waitcnt vmcnt(1)
	v_mov_b32_e32 v36, v20
	s_waitcnt vmcnt(0)
	v_mov_b32_e32 v37, v16
	s_waitcnt lgkmcnt(0)
	v_pk_mul_f32 v[36:37], v[36:37], v[24:25]
	s_nop 0
	v_add_f32_e32 v31, v36, v37

.LBB0_1277:
	s_or_b64 exec, exec, s[18:19]
	s_waitcnt vmcnt(0)
	v_mov_b32_e32 v20, v194
	v_mov_b32_e32 v21, v195
	v_mov_b32_e32 v22, v196
	v_mov_b32_e32 v23, v197
	v_mov_b32_e32 v16, v198
	v_mov_b32_e32 v17, v199
	v_mov_b32_e32 v18, v200
	v_mov_b32_e32 v19, v201
	v_mov_b32_e32 v26, 0
	v_mov_b32_e32 v27, 0
	s_and_saveexec_b64 s[18:19], s[10:11]
	s_cbranch_execz .LBB0_1283
	s_and_saveexec_b64 s[20:21], vcc
	s_xor_b64 s[20:21], exec, s[20:21]
	s_cbranch_execz .LBB0_1280
	s_waitcnt vmcnt(1)
	v_mov_b32_e32 v28, v20
	s_waitcnt vmcnt(0)
	v_mov_b32_e32 v29, v16
	s_waitcnt lgkmcnt(0)
	v_pk_mul_f32 v[28:29], v[28:29], v[24:25]
	s_nop 0
	v_add_f32_e32 v27, v28, v29

.LBB0_1301:
	s_or_b64 exec, exec, s[18:19]
	s_waitcnt vmcnt(1)
	v_or_b32_e32 v20, 40, v43
	v_or_b32_e32 v21, v189, v20
	v_lshlrev_b32_e32 v21, 2, v21
	s_waitcnt vmcnt(0)
	v_cvt_pk_bf16_f32 v19, v29, v28
	ds_bpermute_b32 v29, v21, v44
	ds_bpermute_b32 v28, v21, v45
	v_lshl_or_b32 v20, v20, 4, s16
	v_mov_b32_e32 v21, s17
	v_lshlrev_b64 v[20:21], 2, v[20:21]
	v_cvt_pk_bf16_f32 v16, v31, v30
	v_lshl_add_u64 v[30:31], v[32:33], 0, v[20:21]
	v_cvt_pk_bf16_f32 v17, v37, v36
	v_cvt_pk_bf16_f32 v18, v27, v26
	v_lshl_add_u64 v[36:37], v[34:35], 0, v[20:21]
	s_waitcnt lgkmcnt(2)
	s_waitcnt vmcnt(0)
	v_mov_b32_e32 v24, v202
	v_mov_b32_e32 v25, v203
	v_mov_b32_e32 v26, v204
	v_mov_b32_e32 v27, v205
	v_mov_b32_e32 v20, v206
	v_mov_b32_e32 v21, v207
	v_mov_b32_e32 v22, v208
	v_mov_b32_e32 v23, v209
	v_mov_b32_e32 v38, 0
	v_mov_b32_e32 v39, 0
	s_and_saveexec_b64 s[18:19], s[10:11]
	s_cbranch_execz .LBB0_1307
	s_and_saveexec_b64 s[20:21], vcc
	s_xor_b64 s[20:21], exec, s[20:21]
	s_cbranch_execz .LBB0_1304
	s_waitcnt vmcnt(1)
	v_mov_b32_e32 v40, v24
	s_waitcnt vmcnt(0)
	v_mov_b32_e32 v41, v20
	s_waitcnt lgkmcnt(0)
	v_pk_mul_f32 v[40:41], v[40:41], v[28:29]
	s_nop 0
	v_add_f32_e32 v39, v40, v41

.LBB0_1325:
	s_or_b64 exec, exec, s[18:19]
	s_waitcnt vmcnt(0)
	v_mov_b32_e32 v24, v210
	v_mov_b32_e32 v25, v211
	v_mov_b32_e32 v26, v212
	v_mov_b32_e32 v27, v213
	v_mov_b32_e32 v20, v214
	v_mov_b32_e32 v21, v215
	v_mov_b32_e32 v22, v216
	v_mov_b32_e32 v23, v217
	v_mov_b32_e32 v30, 0
	v_mov_b32_e32 v31, 0
	s_and_saveexec_b64 s[18:19], s[10:11]
	s_cbranch_execz .LBB0_1331
	s_and_saveexec_b64 s[20:21], vcc
	s_xor_b64 s[20:21], exec, s[20:21]
	s_cbranch_execz .LBB0_1328
	s_waitcnt vmcnt(1)
	v_mov_b32_e32 v36, v24
	s_waitcnt vmcnt(0)
	v_mov_b32_e32 v37, v20
	s_waitcnt lgkmcnt(0)
	v_pk_mul_f32 v[36:37], v[36:37], v[28:29]
	s_nop 0
	v_add_f32_e32 v31, v36, v37

.LBB0_1349:
	s_or_b64 exec, exec, s[18:19]
	s_waitcnt vmcnt(1)
	v_or_b32_e32 v24, 48, v43
	v_or_b32_e32 v25, v189, v24
	v_lshlrev_b32_e32 v25, 2, v25
	s_waitcnt vmcnt(0)
	v_cvt_pk_bf16_f32 v23, v37, v36
	ds_bpermute_b32 v37, v25, v44
	ds_bpermute_b32 v36, v25, v45
	v_lshl_or_b32 v24, v24, 4, s16
	v_mov_b32_e32 v25, s17
	v_lshlrev_b64 v[24:25], 2, v[24:25]
	v_cvt_pk_bf16_f32 v20, v39, v38
	v_lshl_add_u64 v[38:39], v[32:33], 0, v[24:25]
	v_cvt_pk_bf16_f32 v21, v41, v40
	v_cvt_pk_bf16_f32 v22, v31, v30
	v_lshl_add_u64 v[40:41], v[34:35], 0, v[24:25]
	s_waitcnt lgkmcnt(2)
	s_waitcnt vmcnt(0)
	v_mov_b32_e32 v28, v218
	v_mov_b32_e32 v29, v219
	v_mov_b32_e32 v30, v220
	v_mov_b32_e32 v31, v221
	v_mov_b32_e32 v24, v222
	v_mov_b32_e32 v25, v223
	v_mov_b32_e32 v26, v224
	v_mov_b32_e32 v27, v225
	v_mov_b32_e32 v46, 0
	v_mov_b32_e32 v47, 0
	s_and_saveexec_b64 s[18:19], s[10:11]
	s_cbranch_execz .LBB0_1355
	s_and_saveexec_b64 s[20:21], vcc
	s_xor_b64 s[20:21], exec, s[20:21]
	s_cbranch_execz .LBB0_1352
	s_waitcnt vmcnt(1)
	v_mov_b32_e32 v48, v28
	s_waitcnt vmcnt(0)
	v_mov_b32_e32 v49, v24
	s_waitcnt lgkmcnt(0)
	v_pk_mul_f32 v[48:49], v[48:49], v[36:37]
	s_nop 0
	v_add_f32_e32 v47, v48, v49

.LBB0_1373:
	s_or_b64 exec, exec, s[18:19]
	s_waitcnt vmcnt(0)
	v_mov_b32_e32 v28, v226
	v_mov_b32_e32 v29, v227
	v_mov_b32_e32 v30, v228
	v_mov_b32_e32 v31, v229
	v_mov_b32_e32 v24, v230
	v_mov_b32_e32 v25, v231
	v_mov_b32_e32 v26, v232
	v_mov_b32_e32 v27, v233
	v_mov_b32_e32 v38, 0
	v_mov_b32_e32 v39, 0
	s_and_saveexec_b64 s[18:19], s[10:11]
	s_cbranch_execz .LBB0_1379
	s_and_saveexec_b64 s[20:21], vcc
	s_xor_b64 s[20:21], exec, s[20:21]
	s_cbranch_execz .LBB0_1376
	s_waitcnt vmcnt(1)
	v_mov_b32_e32 v40, v28
	s_waitcnt vmcnt(0)
	v_mov_b32_e32 v41, v24
	s_waitcnt lgkmcnt(0)
	v_pk_mul_f32 v[40:41], v[40:41], v[36:37]
	s_nop 0
	v_add_f32_e32 v39, v40, v41

.LBB0_1397:
	s_or_b64 exec, exec, s[18:19]
	s_waitcnt vmcnt(1)
	v_or_b32_e32 v28, 56, v43
	v_or_b32_e32 v29, v189, v28
	v_lshlrev_b32_e32 v29, 2, v29
	s_waitcnt lgkmcnt(1)
	ds_bpermute_b32 v37, v29, v44
	s_waitcnt lgkmcnt(1)
	ds_bpermute_b32 v36, v29, v45
	v_lshl_or_b32 v28, v28, 4, s16
	v_mov_b32_e32 v29, s17
	v_lshlrev_b64 v[28:29], 2, v[28:29]
	s_waitcnt vmcnt(0)
	v_cvt_pk_bf16_f32 v26, v39, v38
	v_lshl_add_u64 v[38:39], v[32:33], 0, v[28:29]
	v_cvt_pk_bf16_f32 v27, v41, v40
	v_lshl_add_u64 v[40:41], v[34:35], 0, v[28:29]
	s_waitcnt vmcnt(0)
	v_mov_b32_e32 v32, v234
	v_mov_b32_e32 v33, v235
	v_mov_b32_e32 v34, v236
	v_mov_b32_e32 v35, v237
	v_mov_b32_e32 v28, v238
	v_mov_b32_e32 v29, v239
	v_mov_b32_e32 v30, v240
	v_mov_b32_e32 v31, v241
	v_mov_b32_e32 v43, 0
	v_mov_b32_e32 v44, 0
	v_cvt_pk_bf16_f32 v24, v47, v46
	v_cvt_pk_bf16_f32 v25, v49, v48
	s_and_saveexec_b64 s[18:19], s[10:11]
	s_cbranch_execz .LBB0_1403
	s_and_saveexec_b64 s[20:21], vcc
	s_xor_b64 s[20:21], exec, s[20:21]
	s_cbranch_execz .LBB0_1400
	s_waitcnt vmcnt(1)
	v_mov_b32_e32 v44, v32
	s_waitcnt vmcnt(0)
	v_mov_b32_e32 v45, v28
	s_waitcnt lgkmcnt(0)
	v_pk_mul_f32 v[44:45], v[44:45], v[36:37]
	s_nop 0
	v_add_f32_e32 v44, v44, v45

.LBB0_1421:
	s_or_b64 exec, exec, s[18:19]
	s_waitcnt vmcnt(0)
	v_mov_b32_e32 v32, v242
	v_mov_b32_e32 v33, v243
	v_mov_b32_e32 v34, v244
	v_mov_b32_e32 v35, v245
	v_mov_b32_e32 v28, v246
	v_mov_b32_e32 v29, v247
	v_mov_b32_e32 v30, v248
	v_mov_b32_e32 v31, v249
	v_mov_b32_e32 v38, 0
	v_mov_b32_e32 v39, 0
	s_and_saveexec_b64 s[18:19], s[10:11]
	s_cbranch_execz .LBB0_1427
	s_and_saveexec_b64 s[20:21], vcc
	s_xor_b64 s[20:21], exec, s[20:21]
	s_cbranch_execz .LBB0_1424
	s_waitcnt vmcnt(1)
	v_mov_b32_e32 v40, v32
	s_waitcnt vmcnt(0)
	v_mov_b32_e32 v41, v28
	s_waitcnt lgkmcnt(0)
	v_pk_mul_f32 v[40:41], v[40:41], v[36:37]
	s_nop 0
	v_add_f32_e32 v39, v40, v41
